# full combination with the GQA lazy-rescale exponent made consistent across the two half-waves (rare path verified by forcing it)
# speedup vs baseline: 1.0098x; 1.0028x over previous
.Lgqa_rare0:
	v_mov_b32_e32 v92, v91
	s_nop 1
	v_permlane32_swap_b32_e32 v91, v92
	v_max_f32_e32 v91, v91, v92
	v_frexp_exp_i32_f32_e32 v92, v91
	v_sub_u32_e32 v181, 0, v92
	v_cvt_f32_i32_e32 v179, v92
	v_ldexp_f32 v178, 1.0, v181
	v_pk_mul_f32 v[0:1], v[0:1], v[178:179] op_sel_hi:[1,0]
	v_pk_mul_f32 v[2:3], v[2:3], v[178:179] op_sel_hi:[1,0]
	v_pk_mul_f32 v[4:5], v[4:5], v[178:179] op_sel_hi:[1,0]
	v_pk_mul_f32 v[6:7], v[6:7], v[178:179] op_sel_hi:[1,0]
	v_pk_mul_f32 v[8:9], v[8:9], v[178:179] op_sel_hi:[1,0]
	v_pk_mul_f32 v[10:11], v[10:11], v[178:179] op_sel_hi:[1,0]
	v_pk_mul_f32 v[12:13], v[12:13], v[178:179] op_sel_hi:[1,0]
	v_pk_mul_f32 v[14:15], v[14:15], v[178:179] op_sel_hi:[1,0]
	v_pk_mul_f32 v[16:17], v[16:17], v[178:179] op_sel_hi:[1,0]
	v_pk_mul_f32 v[18:19], v[18:19], v[178:179] op_sel_hi:[1,0]
	v_pk_mul_f32 v[20:21], v[20:21], v[178:179] op_sel_hi:[1,0]
	v_pk_mul_f32 v[22:23], v[22:23], v[178:179] op_sel_hi:[1,0]
	v_pk_mul_f32 v[24:25], v[24:25], v[178:179] op_sel_hi:[1,0]
	v_pk_mul_f32 v[26:27], v[26:27], v[178:179] op_sel_hi:[1,0]
	v_pk_mul_f32 v[28:29], v[28:29], v[178:179] op_sel_hi:[1,0]
	v_pk_mul_f32 v[30:31], v[30:31], v[178:179] op_sel_hi:[1,0]
	v_pk_mul_f32 v[198:199], v[198:199], v[178:179] op_sel_hi:[1,0]
	v_pk_mul_f32 v[248:249], v[248:249], v[178:179] op_sel_hi:[1,0]
	v_sub_f32_e32 v182, v182, v179
	v_sub_f32_e32 v183, v183, v179
	v_sub_f32_e32 v184, v184, v179
	v_sub_f32_e32 v185, v185, v179
	v_sub_f32_e32 v186, v186, v179
	v_sub_f32_e32 v187, v187, v179
	v_sub_f32_e32 v188, v188, v179
	v_sub_f32_e32 v189, v189, v179
	v_sub_f32_e32 v190, v190, v179
	v_sub_f32_e32 v191, v191, v179
	v_sub_f32_e32 v192, v192, v179
	v_sub_f32_e32 v193, v193, v179
	v_sub_f32_e32 v194, v194, v179
	v_sub_f32_e32 v195, v195, v179
	v_sub_f32_e32 v196, v196, v179
	v_sub_f32_e32 v197, v197, v179
	v_sub_f32_e32 v48, v48, v179
	v_sub_f32_e32 v49, v49, v179
	v_sub_f32_e32 v50, v50, v179
	v_sub_f32_e32 v51, v51, v179
	v_sub_f32_e32 v52, v52, v179
	v_sub_f32_e32 v53, v53, v179
	v_sub_f32_e32 v54, v54, v179
	v_sub_f32_e32 v55, v55, v179
	v_sub_f32_e32 v56, v56, v179
	v_sub_f32_e32 v57, v57, v179
	v_sub_f32_e32 v58, v58, v179
	v_sub_f32_e32 v59, v59, v179
	v_sub_f32_e32 v60, v60, v179
	v_sub_f32_e32 v61, v61, v179
	v_sub_f32_e32 v62, v62, v179
	v_sub_f32_e32 v63, v63, v179
	v_sub_f32_e32 v32, v32, v179
	v_sub_f32_e32 v33, v33, v179
	v_sub_f32_e32 v34, v34, v179
	v_sub_f32_e32 v35, v35, v179
	v_sub_f32_e32 v36, v36, v179
	v_sub_f32_e32 v37, v37, v179
	v_sub_f32_e32 v38, v38, v179
	v_sub_f32_e32 v39, v39, v179
	v_sub_f32_e32 v40, v40, v179
	v_sub_f32_e32 v41, v41, v179
	v_sub_f32_e32 v42, v42, v179
	v_sub_f32_e32 v43, v43, v179
	v_sub_f32_e32 v44, v44, v179
	v_sub_f32_e32 v45, v45, v179
	v_sub_f32_e32 v46, v46, v179
	v_sub_f32_e32 v47, v47, v179
	s_branch .Lgqa_rb0
.Lgqa_rare1:
	v_mov_b32_e32 v92, v91
	s_nop 1
	v_permlane32_swap_b32_e32 v91, v92
	v_max_f32_e32 v91, v91, v92
	v_frexp_exp_i32_f32_e32 v92, v91
	v_sub_u32_e32 v181, 0, v92
	v_cvt_f32_i32_e32 v179, v92
	v_ldexp_f32 v178, 1.0, v181
	v_pk_mul_f32 v[0:1], v[0:1], v[178:179] op_sel_hi:[1,0]
	v_pk_mul_f32 v[2:3], v[2:3], v[178:179] op_sel_hi:[1,0]
	v_pk_mul_f32 v[4:5], v[4:5], v[178:179] op_sel_hi:[1,0]
	v_pk_mul_f32 v[6:7], v[6:7], v[178:179] op_sel_hi:[1,0]
	v_pk_mul_f32 v[8:9], v[8:9], v[178:179] op_sel_hi:[1,0]
	v_pk_mul_f32 v[10:11], v[10:11], v[178:179] op_sel_hi:[1,0]
	v_pk_mul_f32 v[12:13], v[12:13], v[178:179] op_sel_hi:[1,0]
	v_pk_mul_f32 v[14:15], v[14:15], v[178:179] op_sel_hi:[1,0]
	v_pk_mul_f32 v[16:17], v[16:17], v[178:179] op_sel_hi:[1,0]
	v_pk_mul_f32 v[18:19], v[18:19], v[178:179] op_sel_hi:[1,0]
	v_pk_mul_f32 v[20:21], v[20:21], v[178:179] op_sel_hi:[1,0]
	v_pk_mul_f32 v[22:23], v[22:23], v[178:179] op_sel_hi:[1,0]
	v_pk_mul_f32 v[24:25], v[24:25], v[178:179] op_sel_hi:[1,0]
	v_pk_mul_f32 v[26:27], v[26:27], v[178:179] op_sel_hi:[1,0]
	v_pk_mul_f32 v[28:29], v[28:29], v[178:179] op_sel_hi:[1,0]
	v_pk_mul_f32 v[30:31], v[30:31], v[178:179] op_sel_hi:[1,0]
	v_pk_mul_f32 v[198:199], v[198:199], v[178:179] op_sel_hi:[1,0]
	v_pk_mul_f32 v[248:249], v[248:249], v[178:179] op_sel_hi:[1,0]
	v_sub_f32_e32 v182, v182, v179
	v_sub_f32_e32 v183, v183, v179
	v_sub_f32_e32 v184, v184, v179
	v_sub_f32_e32 v185, v185, v179
	v_sub_f32_e32 v186, v186, v179
	v_sub_f32_e32 v187, v187, v179
	v_sub_f32_e32 v188, v188, v179
	v_sub_f32_e32 v189, v189, v179
	v_sub_f32_e32 v190, v190, v179
	v_sub_f32_e32 v191, v191, v179
	v_sub_f32_e32 v192, v192, v179
	v_sub_f32_e32 v193, v193, v179
	v_sub_f32_e32 v194, v194, v179
	v_sub_f32_e32 v195, v195, v179
	v_sub_f32_e32 v196, v196, v179
	v_sub_f32_e32 v197, v197, v179
	v_sub_f32_e32 v232, v232, v179
	v_sub_f32_e32 v233, v233, v179
	v_sub_f32_e32 v234, v234, v179
	v_sub_f32_e32 v235, v235, v179
	v_sub_f32_e32 v236, v236, v179
	v_sub_f32_e32 v237, v237, v179
	v_sub_f32_e32 v238, v238, v179
	v_sub_f32_e32 v239, v239, v179
	v_sub_f32_e32 v240, v240, v179
	v_sub_f32_e32 v241, v241, v179
	v_sub_f32_e32 v242, v242, v179
	v_sub_f32_e32 v243, v243, v179
	v_sub_f32_e32 v244, v244, v179
	v_sub_f32_e32 v245, v245, v179
	v_sub_f32_e32 v246, v246, v179
	v_sub_f32_e32 v247, v247, v179
	v_sub_f32_e32 v216, v216, v179
	v_sub_f32_e32 v217, v217, v179
	v_sub_f32_e32 v218, v218, v179
	v_sub_f32_e32 v219, v219, v179
	v_sub_f32_e32 v220, v220, v179
	v_sub_f32_e32 v221, v221, v179
	v_sub_f32_e32 v222, v222, v179
	v_sub_f32_e32 v223, v223, v179
	v_sub_f32_e32 v224, v224, v179
	v_sub_f32_e32 v225, v225, v179
	v_sub_f32_e32 v226, v226, v179
	v_sub_f32_e32 v227, v227, v179
	v_sub_f32_e32 v228, v228, v179
	v_sub_f32_e32 v229, v229, v179
	v_sub_f32_e32 v230, v230, v179
	v_sub_f32_e32 v231, v231, v179
	s_branch .Lgqa_rb1
